# v37 variant: early write-backs by the 6th-from-last and the 2nd-to-last arriver of each XCD
# baseline (speedup 1.0000x reference)
; __device__ __forceinline__ unsigned xb_ld(unsigned* p)              { return __hip_atomic_load(p, __ATOMIC_RELAXED, __HIP_MEMORY_SCOPE_AGENT); }
; __device__ __forceinline__ unsigned xb_add(unsigned* p, unsigned v) { return __hip_atomic_fetch_add(p, v, __ATOMIC_RELAXED, __HIP_MEMORY_SCOPE_AGENT); }
; #define XB_SPIN(cond, bar) do { unsigned _sp = 0; while (cond) { __builtin_amdgcn_s_sleep(1); \
;     if ((++_sp & 255u) == 0u) { if (xb_ld(&(bar)[XB_TMO])) break; if (_sp > XB_SPIN_CAP) { atomicAdd(&(bar)[XB_TMO], 1u); break; } } } } while (0)
; __device__ __forceinline__ void xcd_barrier(const XcdBarrier& b) {
;     ...
;         const unsigned old = xb_add(&bar[XB_XSUB(b.x)], 1u);
;         const unsigned gen = old / nloc;
;         if (old + 1u == (gen + 1u) * nloc) {
;             __builtin_amdgcn_fence(__ATOMIC_RELEASE, "agent");
;             asm volatile("s_waitcnt vmcnt(0)" ::: "memory");
;             const unsigned og = xb_add(&bar[XB_TOP], 1u);
;             const unsigned tg = og / nx;
;             if (og + 1u == (tg + 1u) * nx) xb_add(&bar[XB_TOPGEN], 1u);
;             else XB_SPIN(xb_ld(&bar[XB_TOPGEN]) == tg, bar);
;             __builtin_amdgcn_fence(__ATOMIC_ACQUIRE, "agent");
;             xb_add(&bar[XB_XGEN(b.x)], 1u);
;             asm volatile("s_waitcnt vmcnt(0)" ::: "memory");
;         } else {
;             XB_SPIN(xb_ld(&bar[XB_XGEN(b.x)]) == gen, bar);
.LBB0_117:
	s_or_b64 exec, exec, s[14:15]
	buffer_inv sc1
	v_cvt_f32_u32_e32 v4, v2
	s_waitcnt vmcnt(1)
	v_readfirstlane_b32 s12, v3
	v_sub_u32_e32 v3, 0, v2
	v_rcp_iflag_f32_e32 v4, v4
	v_add_u32_e32 v5, s12, v1
	v_mul_f32_e32 v4, 0x4f7ffffe, v4
	v_cvt_u32_f32_e32 v4, v4
	v_mul_lo_u32 v1, v3, v4
	v_mul_hi_u32 v1, v4, v1
	v_add_u32_e32 v1, v4, v1
	v_mul_hi_u32 v1, v5, v1
	v_mul_lo_u32 v3, v1, v2
	v_sub_u32_e32 v3, v5, v3
	v_add_u32_e32 v4, 1, v1
	v_cmp_ge_u32_e32 vcc, v3, v2
	s_nop 1
	v_cndmask_b32_e32 v1, v1, v4, vcc
	v_sub_u32_e32 v4, v3, v2
	v_cndmask_b32_e32 v3, v3, v4, vcc
	v_add_u32_e32 v4, 1, v1
	v_cmp_ge_u32_e32 vcc, v3, v2
	v_add_u32_e32 v3, 1, v5
	s_nop 0
	v_cndmask_b32_e32 v1, v1, v4, vcc
	v_mul_lo_u32 v4, v2, v1
	v_add_u32_e32 v2, v4, v2
	v_cmp_ne_u32_e32 vcc, v3, v2
	s_and_saveexec_b64 s[12:13], vcc
	s_xor_b64 s[12:13], exec, s[12:13]
	s_cbranch_execz .LBB0_131
	v_sub_u32_e32 v251, v2, v3
	v_cmp_eq_u32_e32 vcc, 6, v251
	s_cbranch_vccnz .Lbar_early_0
	v_cmp_eq_u32_e32 vcc, 1, v251
	s_cbranch_vccz .Lbar_noearly_0

; __device__ __forceinline__ unsigned xb_ld(unsigned* p)              { return __hip_atomic_load(p, __ATOMIC_RELAXED, __HIP_MEMORY_SCOPE_AGENT); }
; __device__ __forceinline__ unsigned xb_add(unsigned* p, unsigned v) { return __hip_atomic_fetch_add(p, v, __ATOMIC_RELAXED, __HIP_MEMORY_SCOPE_AGENT); }
; #define XB_SPIN(cond, bar) do { unsigned _sp = 0; while (cond) { __builtin_amdgcn_s_sleep(1); \
;     if ((++_sp & 255u) == 0u) { if (xb_ld(&(bar)[XB_TMO])) break; if (_sp > XB_SPIN_CAP) { atomicAdd(&(bar)[XB_TMO], 1u); break; } } } } while (0)
; __device__ __forceinline__ void xcd_barrier(const XcdBarrier& b) {
;     ...
;         const unsigned old = xb_add(&bar[XB_XSUB(b.x)], 1u);
;         const unsigned gen = old / nloc;
;         if (old + 1u == (gen + 1u) * nloc) {
;             __builtin_amdgcn_fence(__ATOMIC_RELEASE, "agent");
;             asm volatile("s_waitcnt vmcnt(0)" ::: "memory");
;             const unsigned og = xb_add(&bar[XB_TOP], 1u);
;             const unsigned tg = og / nx;
;             if (og + 1u == (tg + 1u) * nx) xb_add(&bar[XB_TOPGEN], 1u);
;             else XB_SPIN(xb_ld(&bar[XB_TOPGEN]) == tg, bar);
;             __builtin_amdgcn_fence(__ATOMIC_ACQUIRE, "agent");
;             xb_add(&bar[XB_XGEN(b.x)], 1u);
;             asm volatile("s_waitcnt vmcnt(0)" ::: "memory");
;         } else {
;             XB_SPIN(xb_ld(&bar[XB_XGEN(b.x)]) == gen, bar);
.LBB0_328:
	s_or_b64 exec, exec, s[12:13]
	buffer_inv sc1
	v_cvt_f32_u32_e32 v4, v2
	s_waitcnt vmcnt(1)
	v_readfirstlane_b32 s10, v3
	v_sub_u32_e32 v3, 0, v2
	v_rcp_iflag_f32_e32 v4, v4
	v_add_u32_e32 v5, s10, v1
	v_mul_f32_e32 v4, 0x4f7ffffe, v4
	v_cvt_u32_f32_e32 v4, v4
	v_mul_lo_u32 v1, v3, v4
	v_mul_hi_u32 v1, v4, v1
	v_add_u32_e32 v1, v4, v1
	v_mul_hi_u32 v1, v5, v1
	v_mul_lo_u32 v3, v1, v2
	v_sub_u32_e32 v3, v5, v3
	v_add_u32_e32 v4, 1, v1
	v_cmp_ge_u32_e32 vcc, v3, v2
	s_nop 1
	v_cndmask_b32_e32 v1, v1, v4, vcc
	v_sub_u32_e32 v4, v3, v2
	v_cndmask_b32_e32 v3, v3, v4, vcc
	v_add_u32_e32 v4, 1, v1
	v_cmp_ge_u32_e32 vcc, v3, v2
	v_add_u32_e32 v3, 1, v5
	s_nop 0
	v_cndmask_b32_e32 v1, v1, v4, vcc
	v_mul_lo_u32 v4, v2, v1
	v_add_u32_e32 v2, v4, v2
	v_cmp_ne_u32_e32 vcc, v3, v2
	s_and_saveexec_b64 s[10:11], vcc
	s_xor_b64 s[10:11], exec, s[10:11]
	s_cbranch_execz .LBB0_342
	v_sub_u32_e32 v251, v2, v3
	v_cmp_eq_u32_e32 vcc, 6, v251
	s_cbranch_vccnz .Lbar_early_1
	v_cmp_eq_u32_e32 vcc, 1, v251
	s_cbranch_vccz .Lbar_noearly_1

; __device__ __forceinline__ unsigned xb_ld(unsigned* p)              { return __hip_atomic_load(p, __ATOMIC_RELAXED, __HIP_MEMORY_SCOPE_AGENT); }
; __device__ __forceinline__ unsigned xb_add(unsigned* p, unsigned v) { return __hip_atomic_fetch_add(p, v, __ATOMIC_RELAXED, __HIP_MEMORY_SCOPE_AGENT); }
; #define XB_SPIN(cond, bar) do { unsigned _sp = 0; while (cond) { __builtin_amdgcn_s_sleep(1); \
;     if ((++_sp & 255u) == 0u) { if (xb_ld(&(bar)[XB_TMO])) break; if (_sp > XB_SPIN_CAP) { atomicAdd(&(bar)[XB_TMO], 1u); break; } } } } while (0)
; __device__ __forceinline__ void xcd_barrier(const XcdBarrier& b) {
;     ...
;         const unsigned old = xb_add(&bar[XB_XSUB(b.x)], 1u);
;         const unsigned gen = old / nloc;
;         if (old + 1u == (gen + 1u) * nloc) {
;             __builtin_amdgcn_fence(__ATOMIC_RELEASE, "agent");
;             asm volatile("s_waitcnt vmcnt(0)" ::: "memory");
;             const unsigned og = xb_add(&bar[XB_TOP], 1u);
;             const unsigned tg = og / nx;
;             if (og + 1u == (tg + 1u) * nx) xb_add(&bar[XB_TOPGEN], 1u);
;             else XB_SPIN(xb_ld(&bar[XB_TOPGEN]) == tg, bar);
;             __builtin_amdgcn_fence(__ATOMIC_ACQUIRE, "agent");
;             xb_add(&bar[XB_XGEN(b.x)], 1u);
;             asm volatile("s_waitcnt vmcnt(0)" ::: "memory");
;         } else {
;             XB_SPIN(xb_ld(&bar[XB_XGEN(b.x)]) == gen, bar);
.LBB0_419:
	s_or_b64 exec, exec, s[22:23]
	buffer_inv sc1
	v_cvt_f32_u32_e32 v4, v2
	s_waitcnt vmcnt(1)
	v_readfirstlane_b32 s11, v3
	v_sub_u32_e32 v3, 0, v2
	v_rcp_iflag_f32_e32 v4, v4
	v_add_u32_e32 v5, s11, v1
	v_mul_f32_e32 v4, 0x4f7ffffe, v4
	v_cvt_u32_f32_e32 v4, v4
	v_mul_lo_u32 v1, v3, v4
	v_mul_hi_u32 v1, v4, v1
	v_add_u32_e32 v1, v4, v1
	v_mul_hi_u32 v1, v5, v1
	v_mul_lo_u32 v3, v1, v2
	v_sub_u32_e32 v3, v5, v3
	v_add_u32_e32 v4, 1, v1
	v_cmp_ge_u32_e32 vcc, v3, v2
	s_nop 1
	v_cndmask_b32_e32 v1, v1, v4, vcc
	v_sub_u32_e32 v4, v3, v2
	v_cndmask_b32_e32 v3, v3, v4, vcc
	v_add_u32_e32 v4, 1, v1
	v_cmp_ge_u32_e32 vcc, v3, v2
	v_add_u32_e32 v3, 1, v5
	s_nop 0
	v_cndmask_b32_e32 v1, v1, v4, vcc
	v_mul_lo_u32 v4, v2, v1
	v_add_u32_e32 v2, v4, v2
	v_cmp_ne_u32_e32 vcc, v3, v2
	s_and_saveexec_b64 s[12:13], vcc
	s_xor_b64 s[22:23], exec, s[12:13]
	s_cbranch_execz .LBB0_433
	v_sub_u32_e32 v251, v2, v3
	v_cmp_eq_u32_e32 vcc, 6, v251
	s_cbranch_vccnz .Lbar_early_2
	v_cmp_eq_u32_e32 vcc, 1, v251
	s_cbranch_vccz .Lbar_noearly_2

; __device__ __forceinline__ unsigned xb_ld(unsigned* p)              { return __hip_atomic_load(p, __ATOMIC_RELAXED, __HIP_MEMORY_SCOPE_AGENT); }
; __device__ __forceinline__ unsigned xb_add(unsigned* p, unsigned v) { return __hip_atomic_fetch_add(p, v, __ATOMIC_RELAXED, __HIP_MEMORY_SCOPE_AGENT); }
; #define XB_SPIN(cond, bar) do { unsigned _sp = 0; while (cond) { __builtin_amdgcn_s_sleep(1); \
;     if ((++_sp & 255u) == 0u) { if (xb_ld(&(bar)[XB_TMO])) break; if (_sp > XB_SPIN_CAP) { atomicAdd(&(bar)[XB_TMO], 1u); break; } } } } while (0)
; __device__ __forceinline__ void xcd_barrier(const XcdBarrier& b) {
;     ...
;         const unsigned old = xb_add(&bar[XB_XSUB(b.x)], 1u);
;         const unsigned gen = old / nloc;
;         if (old + 1u == (gen + 1u) * nloc) {
;             __builtin_amdgcn_fence(__ATOMIC_RELEASE, "agent");
;             asm volatile("s_waitcnt vmcnt(0)" ::: "memory");
;             const unsigned og = xb_add(&bar[XB_TOP], 1u);
;             const unsigned tg = og / nx;
;             if (og + 1u == (tg + 1u) * nx) xb_add(&bar[XB_TOPGEN], 1u);
;             else XB_SPIN(xb_ld(&bar[XB_TOPGEN]) == tg, bar);
;             __builtin_amdgcn_fence(__ATOMIC_ACQUIRE, "agent");
;             xb_add(&bar[XB_XGEN(b.x)], 1u);
;             asm volatile("s_waitcnt vmcnt(0)" ::: "memory");
;         } else {
;             XB_SPIN(xb_ld(&bar[XB_XGEN(b.x)]) == gen, bar);
.LBB0_1389:
	s_or_b64 exec, exec, s[22:23]
	buffer_inv sc1
	v_cvt_f32_u32_e32 v4, v2
	s_waitcnt vmcnt(1)
	v_readfirstlane_b32 s6, v3
	v_sub_u32_e32 v3, 0, v2
	v_rcp_iflag_f32_e32 v4, v4
	v_add_u32_e32 v5, s6, v1
	v_mul_f32_e32 v4, 0x4f7ffffe, v4
	v_cvt_u32_f32_e32 v4, v4
	v_mul_lo_u32 v1, v3, v4
	v_mul_hi_u32 v1, v4, v1
	v_add_u32_e32 v1, v4, v1
	v_mul_hi_u32 v1, v5, v1
	v_mul_lo_u32 v3, v1, v2
	v_sub_u32_e32 v3, v5, v3
	v_add_u32_e32 v4, 1, v1
	v_cmp_ge_u32_e32 vcc, v3, v2
	s_nop 1
	v_cndmask_b32_e32 v1, v1, v4, vcc
	v_sub_u32_e32 v4, v3, v2
	v_cndmask_b32_e32 v3, v3, v4, vcc
	v_add_u32_e32 v4, 1, v1
	v_cmp_ge_u32_e32 vcc, v3, v2
	v_add_u32_e32 v3, 1, v5
	s_nop 0
	v_cndmask_b32_e32 v1, v1, v4, vcc
	v_mul_lo_u32 v4, v2, v1
	v_add_u32_e32 v2, v4, v2
	v_cmp_ne_u32_e32 vcc, v3, v2
	s_and_saveexec_b64 s[16:17], vcc
	s_xor_b64 s[22:23], exec, s[16:17]
	s_cbranch_execz .LBB0_1403
	v_sub_u32_e32 v251, v2, v3
	v_cmp_eq_u32_e32 vcc, 6, v251
	s_cbranch_vccnz .Lbar_early_8
	v_cmp_eq_u32_e32 vcc, 1, v251
	s_cbranch_vccz .Lbar_noearly_8

; __device__ __forceinline__ unsigned xb_ld(unsigned* p)              { return __hip_atomic_load(p, __ATOMIC_RELAXED, __HIP_MEMORY_SCOPE_AGENT); }
; __device__ __forceinline__ unsigned xb_add(unsigned* p, unsigned v) { return __hip_atomic_fetch_add(p, v, __ATOMIC_RELAXED, __HIP_MEMORY_SCOPE_AGENT); }
; #define XB_SPIN(cond, bar) do { unsigned _sp = 0; while (cond) { __builtin_amdgcn_s_sleep(1); \
;     if ((++_sp & 255u) == 0u) { if (xb_ld(&(bar)[XB_TMO])) break; if (_sp > XB_SPIN_CAP) { atomicAdd(&(bar)[XB_TMO], 1u); break; } } } } while (0)
; __device__ __forceinline__ void xcd_barrier(const XcdBarrier& b) {
;     ...
;         const unsigned old = xb_add(&bar[XB_XSUB(b.x)], 1u);
;         const unsigned gen = old / nloc;
;         if (old + 1u == (gen + 1u) * nloc) {
;             __builtin_amdgcn_fence(__ATOMIC_RELEASE, "agent");
;             asm volatile("s_waitcnt vmcnt(0)" ::: "memory");
;             const unsigned og = xb_add(&bar[XB_TOP], 1u);
;             const unsigned tg = og / nx;
;             if (og + 1u == (tg + 1u) * nx) xb_add(&bar[XB_TOPGEN], 1u);
;             else XB_SPIN(xb_ld(&bar[XB_TOPGEN]) == tg, bar);
;             __builtin_amdgcn_fence(__ATOMIC_ACQUIRE, "agent");
;             xb_add(&bar[XB_XGEN(b.x)], 1u);
;             asm volatile("s_waitcnt vmcnt(0)" ::: "memory");
;         } else {
;             XB_SPIN(xb_ld(&bar[XB_XGEN(b.x)]) == gen, bar);
.LBB0_2162:
	s_or_b64 exec, exec, s[22:23]
	buffer_inv sc1
	v_cvt_f32_u32_e32 v4, v2
	s_waitcnt vmcnt(1)
	v_readfirstlane_b32 s6, v3
	v_sub_u32_e32 v3, 0, v2
	v_rcp_iflag_f32_e32 v4, v4
	v_add_u32_e32 v5, s6, v1
	v_mul_f32_e32 v4, 0x4f7ffffe, v4
	v_cvt_u32_f32_e32 v4, v4
	v_mul_lo_u32 v1, v3, v4
	v_mul_hi_u32 v1, v4, v1
	v_add_u32_e32 v1, v4, v1
	v_mul_hi_u32 v1, v5, v1
	v_mul_lo_u32 v3, v1, v2
	v_sub_u32_e32 v3, v5, v3
	v_add_u32_e32 v4, 1, v1
	v_cmp_ge_u32_e32 vcc, v3, v2
	s_nop 1
	v_cndmask_b32_e32 v1, v1, v4, vcc
	v_sub_u32_e32 v4, v3, v2
	v_cndmask_b32_e32 v3, v3, v4, vcc
	v_add_u32_e32 v4, 1, v1
	v_cmp_ge_u32_e32 vcc, v3, v2
	v_add_u32_e32 v3, 1, v5
	s_nop 0
	v_cndmask_b32_e32 v1, v1, v4, vcc
	v_mul_lo_u32 v4, v2, v1
	v_add_u32_e32 v2, v4, v2
	v_cmp_ne_u32_e32 vcc, v3, v2
	s_and_saveexec_b64 s[14:15], vcc
	s_xor_b64 s[22:23], exec, s[14:15]
	s_cbranch_execz .LBB0_2176
	v_sub_u32_e32 v251, v2, v3
	v_cmp_eq_u32_e32 vcc, 6, v251
	s_cbranch_vccnz .Lbar_early_14
	v_cmp_eq_u32_e32 vcc, 1, v251
	s_cbranch_vccz .Lbar_noearly_14

; __device__ __forceinline__ unsigned xb_ld(unsigned* p)              { return __hip_atomic_load(p, __ATOMIC_RELAXED, __HIP_MEMORY_SCOPE_AGENT); }
; __device__ __forceinline__ unsigned xb_add(unsigned* p, unsigned v) { return __hip_atomic_fetch_add(p, v, __ATOMIC_RELAXED, __HIP_MEMORY_SCOPE_AGENT); }
; #define XB_SPIN(cond, bar) do { unsigned _sp = 0; while (cond) { __builtin_amdgcn_s_sleep(1); \
;     if ((++_sp & 255u) == 0u) { if (xb_ld(&(bar)[XB_TMO])) break; if (_sp > XB_SPIN_CAP) { atomicAdd(&(bar)[XB_TMO], 1u); break; } } } } while (0)
; __device__ __forceinline__ void xcd_barrier(const XcdBarrier& b) {
;     ...
;         const unsigned old = xb_add(&bar[XB_XSUB(b.x)], 1u);
;         const unsigned gen = old / nloc;
;         if (old + 1u == (gen + 1u) * nloc) {
;             __builtin_amdgcn_fence(__ATOMIC_RELEASE, "agent");
;             asm volatile("s_waitcnt vmcnt(0)" ::: "memory");
;             const unsigned og = xb_add(&bar[XB_TOP], 1u);
;             const unsigned tg = og / nx;
;             if (og + 1u == (tg + 1u) * nx) xb_add(&bar[XB_TOPGEN], 1u);
;             else XB_SPIN(xb_ld(&bar[XB_TOPGEN]) == tg, bar);
;             __builtin_amdgcn_fence(__ATOMIC_ACQUIRE, "agent");
;             xb_add(&bar[XB_XGEN(b.x)], 1u);
;             asm volatile("s_waitcnt vmcnt(0)" ::: "memory");
;         } else {
;             XB_SPIN(xb_ld(&bar[XB_XGEN(b.x)]) == gen, bar);
.LBB0_2258:
	s_or_b64 exec, exec, s[22:23]
	buffer_inv sc1
	v_cvt_f32_u32_e32 v4, v2
	s_waitcnt vmcnt(1)
	v_readfirstlane_b32 s11, v3
	v_sub_u32_e32 v3, 0, v2
	v_rcp_iflag_f32_e32 v4, v4
	v_add_u32_e32 v5, s11, v1
	v_mul_f32_e32 v4, 0x4f7ffffe, v4
	v_cvt_u32_f32_e32 v4, v4
	v_mul_lo_u32 v1, v3, v4
	v_mul_hi_u32 v1, v4, v1
	v_add_u32_e32 v1, v4, v1
	v_mul_hi_u32 v1, v5, v1
	v_mul_lo_u32 v3, v1, v2
	v_sub_u32_e32 v3, v5, v3
	v_add_u32_e32 v4, 1, v1
	v_cmp_ge_u32_e32 vcc, v3, v2
	s_nop 1
	v_cndmask_b32_e32 v1, v1, v4, vcc
	v_sub_u32_e32 v4, v3, v2
	v_cndmask_b32_e32 v3, v3, v4, vcc
	v_add_u32_e32 v4, 1, v1
	v_cmp_ge_u32_e32 vcc, v3, v2
	v_add_u32_e32 v3, 1, v5
	s_nop 0
	v_cndmask_b32_e32 v1, v1, v4, vcc
	v_mul_lo_u32 v4, v2, v1
	v_add_u32_e32 v2, v4, v2
	v_cmp_ne_u32_e32 vcc, v3, v2
	s_and_saveexec_b64 s[14:15], vcc
	s_xor_b64 s[22:23], exec, s[14:15]
	s_cbranch_execz .LBB0_2272
	v_sub_u32_e32 v251, v2, v3
	v_cmp_eq_u32_e32 vcc, 6, v251
	s_cbranch_vccnz .Lbar_early_15
	v_cmp_eq_u32_e32 vcc, 1, v251
	s_cbranch_vccz .Lbar_noearly_15

; __device__ __forceinline__ unsigned xb_ld(unsigned* p)              { return __hip_atomic_load(p, __ATOMIC_RELAXED, __HIP_MEMORY_SCOPE_AGENT); }
; __device__ __forceinline__ unsigned xb_add(unsigned* p, unsigned v) { return __hip_atomic_fetch_add(p, v, __ATOMIC_RELAXED, __HIP_MEMORY_SCOPE_AGENT); }
; #define XB_SPIN(cond, bar) do { unsigned _sp = 0; while (cond) { __builtin_amdgcn_s_sleep(1); \
;     if ((++_sp & 255u) == 0u) { if (xb_ld(&(bar)[XB_TMO])) break; if (_sp > XB_SPIN_CAP) { atomicAdd(&(bar)[XB_TMO], 1u); break; } } } } while (0)
; __device__ __forceinline__ void xcd_barrier(const XcdBarrier& b) {
;     ...
;         const unsigned old = xb_add(&bar[XB_XSUB(b.x)], 1u);
;         const unsigned gen = old / nloc;
;         if (old + 1u == (gen + 1u) * nloc) {
;             __builtin_amdgcn_fence(__ATOMIC_RELEASE, "agent");
;             asm volatile("s_waitcnt vmcnt(0)" ::: "memory");
;             const unsigned og = xb_add(&bar[XB_TOP], 1u);
;             const unsigned tg = og / nx;
;             if (og + 1u == (tg + 1u) * nx) xb_add(&bar[XB_TOPGEN], 1u);
;             else XB_SPIN(xb_ld(&bar[XB_TOPGEN]) == tg, bar);
;             __builtin_amdgcn_fence(__ATOMIC_ACQUIRE, "agent");
;             xb_add(&bar[XB_XGEN(b.x)], 1u);
;             asm volatile("s_waitcnt vmcnt(0)" ::: "memory");
;         } else {
;             XB_SPIN(xb_ld(&bar[XB_XGEN(b.x)]) == gen, bar);
.LBB0_2618:
	s_or_b64 exec, exec, s[2:3]
	buffer_inv sc1
	v_cvt_f32_u32_e32 v4, v2
	s_waitcnt vmcnt(1)
	v_readfirstlane_b32 s2, v3
	v_sub_u32_e32 v3, 0, v2
	v_rcp_iflag_f32_e32 v4, v4
	v_add_u32_e32 v5, s2, v1
	v_mul_f32_e32 v4, 0x4f7ffffe, v4
	v_cvt_u32_f32_e32 v4, v4
	v_mul_lo_u32 v1, v3, v4
	v_mul_hi_u32 v1, v4, v1
	v_add_u32_e32 v1, v4, v1
	v_mul_hi_u32 v1, v5, v1
	v_mul_lo_u32 v3, v1, v2
	v_sub_u32_e32 v3, v5, v3
	v_add_u32_e32 v4, 1, v1
	v_cmp_ge_u32_e32 vcc, v3, v2
	s_nop 1
	v_cndmask_b32_e32 v1, v1, v4, vcc
	v_sub_u32_e32 v4, v3, v2
	v_cndmask_b32_e32 v3, v3, v4, vcc
	v_add_u32_e32 v4, 1, v1
	v_cmp_ge_u32_e32 vcc, v3, v2
	v_add_u32_e32 v3, 1, v5
	s_nop 0
	v_cndmask_b32_e32 v1, v1, v4, vcc
	v_mul_lo_u32 v4, v2, v1
	v_add_u32_e32 v2, v4, v2
	v_cmp_ne_u32_e32 vcc, v3, v2
	s_and_saveexec_b64 s[2:3], vcc
	s_xor_b64 s[2:3], exec, s[2:3]
	s_cbranch_execz .LBB0_2632
	v_sub_u32_e32 v251, v2, v3
	v_cmp_eq_u32_e32 vcc, 6, v251
	s_cbranch_vccnz .Lbar_early_17
	v_cmp_eq_u32_e32 vcc, 1, v251
	s_cbranch_vccz .Lbar_noearly_17
